# stack1d + packed v_pk_add_f32 in attention softmax split into scalar v_sub/v_add (instruction selection beside MFMAs)
# speedup vs baseline: 1.0135x; 1.0062x over previous
; __device__ __forceinline__ float fast_exp2(float x) { return __builtin_amdgcn_exp2f(x); }
; template <int MODE>
; __device__ __forceinline__ void attn_unit(const Params& P, int b, int h, int qb, unsigned char* smem) {
;     ...
;       {
;         const f32x2_t m2 = {m_run, m_run};
;         f32x2_t ps2 = {0.f, 0.f};
; #pragma unroll
;         for (int kb = 0; kb < 2; ++kb)
; #pragma unroll
;           for (int i = 0; i < 8; ++i) {
;             f32x2_t t = {sacc[kb][2 * i], sacc[kb][2 * i + 1]};
;             t -= m2;
;             f32x2_t e; e[0] = fast_exp2(t[0]); e[1] = fast_exp2(t[1]);
;             ps2 += e;
;             sacc[kb][2 * i] = e[0]; sacc[kb][2 * i + 1] = e[1];
;           }
;         l_run += ps2[0] + ps2[1];
;       }
;       bf16x8 pf[4];
; #pragma unroll
;       for (int a = 0; a < 4; ++a) {
;         const int kb = a >> 1, o8 = (a & 1) * 8;
;         u32x4 u;
;         u.x = pk_bf16(sacc[kb][o8 + 0], sacc[kb][o8 + 1]); u.y = pk_bf16(sacc[kb][o8 + 2], sacc[kb][o8 + 3]);
;         u.z = pk_bf16(sacc[kb][o8 + 4], sacc[kb][o8 + 5]); u.w = pk_bf16(sacc[kb][o8 + 6], sacc[kb][o8 + 7]);
;         pf[a] = __builtin_bit_cast(bf16x8, u);
;       }
; #pragma unroll
;       for (int db = 0; db < 2; ++db)
; #pragma unroll
;         for (int a = 0; a < 4; ++a) {
;           bf16x8 vf = *(const bf16x8*)(smem + cur + 8192 + (32 * db + r) * 128 + (((2 * a + hi) ^ swz) << 4));
;           oacc[db] = __builtin_amdgcn_mfma_f32_32x32x16_bf16(vf, pf[a], oacc[db], 0, 0, 0);
;         }
.LBB0_853:
	v_sub_f32_e32 v14, v64, v142
	v_sub_f32_e32 v15, v65, v142
	s_nop 0
	v_exp_f32_e32 v94, v14
	v_exp_f32_e32 v95, v15
	v_sub_f32_e32 v14, v66, v142
	v_sub_f32_e32 v15, v67, v142
	s_nop 0
	v_exp_f32_e32 v96, v14
	v_exp_f32_e32 v97, v15
	v_sub_f32_e32 v14, v68, v142
	v_sub_f32_e32 v15, v69, v142
	s_nop 0
	v_exp_f32_e32 v98, v14
	v_exp_f32_e32 v99, v15
	v_sub_f32_e32 v14, v70, v142
	v_sub_f32_e32 v15, v71, v142
	s_nop 0
	v_exp_f32_e32 v100, v14
	v_exp_f32_e32 v101, v15
	v_sub_f32_e32 v14, v72, v142
	v_sub_f32_e32 v15, v73, v142
	s_nop 0
	v_exp_f32_e32 v102, v14
	v_exp_f32_e32 v103, v15
	v_sub_f32_e32 v14, v74, v142
	v_sub_f32_e32 v15, v75, v142
	s_nop 0
	v_exp_f32_e32 v104, v14
	v_exp_f32_e32 v105, v15
	v_sub_f32_e32 v14, v76, v142
	v_sub_f32_e32 v15, v77, v142
	v_sub_f32_e32 v76, v62, v142
	v_sub_f32_e32 v77, v63, v142
	v_exp_f32_e32 v106, v14
	v_exp_f32_e32 v107, v15
	v_sub_f32_e32 v14, v78, v142
	v_sub_f32_e32 v15, v79, v142
	v_exp_f32_e32 v170, v76
	v_exp_f32_e32 v108, v14
	v_exp_f32_e32 v109, v15
	v_sub_f32_e32 v14, v48, v142
	v_sub_f32_e32 v15, v49, v142
	v_exp_f32_e32 v171, v77
	v_exp_f32_e32 v110, v14
	v_exp_f32_e32 v111, v15
	v_sub_f32_e32 v14, v50, v142
	v_sub_f32_e32 v15, v51, v142
	ds_read_b128 v[48:51], v10 offset:8192
	v_exp_f32_e32 v158, v14
	v_exp_f32_e32 v159, v15
	v_sub_f32_e32 v14, v52, v142
	v_sub_f32_e32 v15, v53, v142
	v_cvt_pk_bf16_f32 v52, v94, v95
	v_exp_f32_e32 v160, v14
	v_exp_f32_e32 v161, v15
	v_sub_f32_e32 v14, v54, v142
	v_sub_f32_e32 v15, v55, v142
	v_cvt_pk_bf16_f32 v53, v96, v97
	v_exp_f32_e32 v162, v14
	v_exp_f32_e32 v163, v15
	v_sub_f32_e32 v14, v56, v142
	v_sub_f32_e32 v15, v57, v142
	v_cvt_pk_bf16_f32 v54, v98, v99
	v_exp_f32_e32 v164, v14
	v_exp_f32_e32 v165, v15
	v_sub_f32_e32 v14, v58, v142
	v_sub_f32_e32 v15, v59, v142
	ds_read_b128 v[56:59], v0 offset:8192
	ds_read_b128 v[64:67], v10 offset:12288
	v_cvt_pk_bf16_f32 v55, v100, v101
	ds_read_b128 v[68:71], v12 offset:8192
	ds_read_b128 v[72:75], v0 offset:12288
	s_waitcnt lgkmcnt(4)
	v_mfma_f32_32x32x16_bf16 v[32:47], v[48:51], v[52:55], v[32:47]
	v_cvt_pk_bf16_f32 v48, v102, v103
	v_cvt_pk_bf16_f32 v49, v104, v105
	v_cvt_pk_bf16_f32 v50, v106, v107
	v_cvt_pk_bf16_f32 v51, v108, v109
	v_exp_f32_e32 v166, v14
	v_exp_f32_e32 v167, v15
	v_sub_f32_e32 v14, v60, v142
	v_sub_f32_e32 v15, v61, v142
	s_waitcnt lgkmcnt(2)
	v_mfma_f32_32x32x16_bf16 v[16:31], v[64:67], v[52:55], v[16:31]
	v_exp_f32_e32 v168, v14
	v_exp_f32_e32 v169, v15
	ds_read_b128 v[60:63], v11 offset:8192
	ds_read_b128 v[12:15], v12 offset:12288
	ds_read_b128 v[76:79], v11 offset:12288
	v_add_f32_e32 v10, 0, v94
	v_add_f32_e32 v11, 0, v95
	s_nop 0
	v_add_f32_e32 v10, v96, v10
	v_add_f32_e32 v11, v97, v11
	v_mfma_f32_32x32x16_bf16 v[32:47], v[56:59], v[48:51], v[32:47]
	v_cvt_pk_bf16_f32 v56, v110, v111
	v_cvt_pk_bf16_f32 v57, v158, v159
	v_cvt_pk_bf16_f32 v58, v160, v161
	v_cvt_pk_bf16_f32 v59, v162, v163
	v_add_f32_e64 v10, v98, v10
	v_add_f32_e64 v11, v99, v11
	v_add_f32_e32 v10, v100, v10
	v_add_f32_e32 v11, v101, v11
	s_waitcnt lgkmcnt(3)
	v_mfma_f32_32x32x16_bf16 v[16:31], v[72:75], v[48:51], v[16:31]
	v_add_f32_e64 v10, v102, v10
	v_add_f32_e64 v11, v103, v11
	v_add_f32_e64 v10, v104, v10
	v_add_f32_e64 v11, v105, v11
	v_add_f32_e64 v10, v106, v10
	v_add_f32_e64 v11, v107, v11
	v_add_f32_e32 v10, v108, v10
	v_add_f32_e32 v11, v109, v11
	v_mfma_f32_32x32x16_bf16 v[32:47], v[68:71], v[56:59], v[32:47]
	v_add_f32_e64 v10, v110, v10
	v_add_f32_e64 v11, v111, v11
	v_cvt_pk_bf16_f32 v68, v164, v165
	v_cvt_pk_bf16_f32 v69, v166, v167
	v_cvt_pk_bf16_f32 v70, v168, v169
	v_cvt_pk_bf16_f32 v71, v170, v171
	v_add_f32_e32 v10, v158, v10
	v_add_f32_e32 v11, v159, v11
	s_waitcnt lgkmcnt(1)
	v_mfma_f32_32x32x16_bf16 v[16:31], v[12:15], v[56:59], v[16:31]
	v_add_f32_e64 v10, v160, v10
	v_add_f32_e64 v11, v161, v11
	v_add_f32_e64 v10, v162, v10
	v_add_f32_e64 v11, v163, v11
	v_add_f32_e64 v10, v164, v10
	v_add_f32_e64 v11, v165, v11
	v_add_f32_e32 v10, v166, v10
	v_add_f32_e32 v11, v167, v11
	v_mfma_f32_32x32x16_bf16 v[32:47], v[60:63], v[68:71], v[32:47]
	v_add_f32_e64 v10, v168, v10
	v_add_f32_e64 v11, v169, v11
	v_add_f32_e64 v10, v170, v10
	v_add_f32_e64 v11, v171, v11
	v_add_f32_e32 v0, v10, v11
	v_add_f32_e32 v145, v145, v0
	s_waitcnt lgkmcnt(0)
	v_mfma_f32_32x32x16_bf16 v[16:31], v[76:79], v[68:71], v[16:31]

; __device__ __forceinline__ float fast_exp2(float x) { return __builtin_amdgcn_exp2f(x); }
; template <int MODE>
; __device__ __forceinline__ void attn_unit(const Params& P, int b, int h, int qb, unsigned char* smem) {
;     ...
;       {
;         const f32x2_t m2 = {m_run, m_run};
;         f32x2_t ps2 = {0.f, 0.f};
; #pragma unroll
;         for (int kb = 0; kb < 2; ++kb)
; #pragma unroll
;           for (int i = 0; i < 8; ++i) {
;             f32x2_t t = {sacc[kb][2 * i], sacc[kb][2 * i + 1]};
;             t -= m2;
;             f32x2_t e; e[0] = fast_exp2(t[0]); e[1] = fast_exp2(t[1]);
;             ps2 += e;
;             sacc[kb][2 * i] = e[0]; sacc[kb][2 * i + 1] = e[1];
;           }
;         l_run += ps2[0] + ps2[1];
;       }
;       bf16x8 pf[4];
; #pragma unroll
;       for (int a = 0; a < 4; ++a) {
;         const int kb = a >> 1, o8 = (a & 1) * 8;
;         u32x4 u;
;         u.x = pk_bf16(sacc[kb][o8 + 0], sacc[kb][o8 + 1]); u.y = pk_bf16(sacc[kb][o8 + 2], sacc[kb][o8 + 3]);
;         u.z = pk_bf16(sacc[kb][o8 + 4], sacc[kb][o8 + 5]); u.w = pk_bf16(sacc[kb][o8 + 6], sacc[kb][o8 + 7]);
;         pf[a] = __builtin_bit_cast(bf16x8, u);
;       }
; #pragma unroll
;       for (int db = 0; db < 2; ++db)
; #pragma unroll
;         for (int a = 0; a < 4; ++a) {
;           bf16x8 vf = *(const bf16x8*)(smem + cur + 8192 + (32 * db + r) * 128 + (((2 * a + hi) ^ swz) << 4));
;           oacc[db] = __builtin_amdgcn_mfma_f32_32x32x16_bf16(vf, pf[a], oacc[db], 0, 0, 0);
;         }
.LBB0_862:
	v_sub_f32_e32 v10, v64, v142
	v_sub_f32_e32 v11, v65, v142
	v_sub_f32_e32 v60, v60, v142
	v_sub_f32_e32 v61, v61, v142
	v_exp_f32_e32 v14, v10
	v_exp_f32_e32 v15, v11
	v_sub_f32_e32 v10, v66, v142
	v_sub_f32_e32 v11, v67, v142
	v_exp_f32_e32 v150, v60
	v_exp_f32_e32 v114, v10
	v_exp_f32_e32 v115, v11
	v_sub_f32_e32 v10, v68, v142
	v_sub_f32_e32 v11, v69, v142
	v_exp_f32_e32 v151, v61
	v_exp_f32_e32 v116, v10
	v_exp_f32_e32 v117, v11
	v_sub_f32_e32 v10, v70, v142
	v_sub_f32_e32 v11, v71, v142
	s_nop 0
	v_exp_f32_e32 v118, v10
	v_exp_f32_e32 v119, v11
	v_sub_f32_e32 v10, v72, v142
	v_sub_f32_e32 v11, v73, v142
	s_nop 0
	v_exp_f32_e32 v120, v10
	v_exp_f32_e32 v121, v11
	v_sub_f32_e32 v10, v74, v142
	v_sub_f32_e32 v11, v75, v142
	s_nop 0
	v_exp_f32_e32 v122, v10
	v_exp_f32_e32 v123, v11
	v_sub_f32_e32 v10, v76, v142
	v_sub_f32_e32 v11, v77, v142
	v_sub_f32_e32 v76, v62, v142
	v_sub_f32_e32 v77, v63, v142
	v_exp_f32_e32 v124, v10
	v_exp_f32_e32 v125, v11
	v_sub_f32_e32 v10, v78, v142
	v_sub_f32_e32 v11, v79, v142
	v_exp_f32_e32 v152, v76
	v_exp_f32_e32 v126, v10
	v_exp_f32_e32 v127, v11
	v_sub_f32_e32 v10, v48, v142
	v_sub_f32_e32 v11, v49, v142
	v_cvt_pk_bf16_f32 v48, v14, v15
	v_exp_f32_e32 v128, v10
	v_exp_f32_e32 v129, v11
	v_sub_f32_e32 v10, v50, v142
	v_sub_f32_e32 v11, v51, v142
	v_cvt_pk_bf16_f32 v49, v114, v115
	v_exp_f32_e32 v130, v10
	v_exp_f32_e32 v131, v11
	v_sub_f32_e32 v10, v52, v142
	v_sub_f32_e32 v11, v53, v142
	v_cvt_pk_bf16_f32 v50, v116, v117
	v_exp_f32_e32 v132, v10
	v_exp_f32_e32 v133, v11
	v_sub_f32_e32 v10, v54, v142
	v_sub_f32_e32 v11, v55, v142
	v_cvt_pk_bf16_f32 v51, v118, v119
	v_exp_f32_e32 v134, v10
	v_exp_f32_e32 v135, v11
	v_sub_f32_e32 v10, v56, v142
	v_sub_f32_e32 v11, v57, v142
	v_exp_f32_e32 v153, v77
	v_exp_f32_e32 v136, v10
	v_exp_f32_e32 v137, v11
	v_sub_f32_e32 v10, v58, v142
	v_sub_f32_e32 v11, v59, v142
	s_nop 0
	v_exp_f32_e32 v148, v10
	v_exp_f32_e32 v149, v11
	ds_read_b128 v[10:13], v2 offset:8192
	ds_read_b128 v[52:55], v0 offset:8192
	ds_read_b128 v[56:59], v2 offset:12288
	s_waitcnt lgkmcnt(2)
	v_mfma_f32_32x32x16_bf16 v[96:111], v[10:13], v[48:51], v[96:111]
	ds_read_b128 v[64:67], v4 offset:8192
	ds_read_b128 v[68:71], v0 offset:12288
	v_cvt_pk_bf16_f32 v10, v120, v121
	v_cvt_pk_bf16_f32 v11, v122, v123
	v_cvt_pk_bf16_f32 v12, v124, v125
	v_cvt_pk_bf16_f32 v13, v126, v127
	ds_read_b128 v[60:63], v3 offset:8192
	ds_read_b128 v[72:75], v4 offset:12288
	ds_read_b128 v[76:79], v3 offset:12288
	s_waitcnt lgkmcnt(5)
	v_mfma_f32_32x32x16_bf16 v[80:95], v[56:59], v[48:51], v[80:95]
	v_add_f32_e64 v2, v14, 0
	v_add_f32_e64 v3, v15, 0
	v_add_f32_e64 v2, v114, v2
	v_add_f32_e64 v3, v115, v3
	v_add_f32_e64 v2, v116, v2
	v_add_f32_e64 v3, v117, v3
	v_add_f32_e32 v2, v118, v2
	v_add_f32_e32 v3, v119, v3
	v_mfma_f32_32x32x16_bf16 v[96:111], v[52:55], v[10:13], v[96:111]
	v_add_f32_e64 v2, v120, v2
	v_add_f32_e64 v3, v121, v3
	v_cvt_pk_bf16_f32 v52, v128, v129
	v_add_f32_e64 v2, v122, v2
	v_add_f32_e64 v3, v123, v3
	v_cvt_pk_bf16_f32 v53, v130, v131
	v_add_f32_e32 v2, v124, v2
	v_add_f32_e32 v3, v125, v3
	v_cvt_pk_bf16_f32 v54, v132, v133
	v_add_f32_e32 v2, v126, v2
	v_add_f32_e32 v3, v127, v3
	s_waitcnt lgkmcnt(3)
	v_mfma_f32_32x32x16_bf16 v[80:95], v[68:71], v[10:13], v[80:95]
	v_cvt_pk_bf16_f32 v55, v134, v135
	v_add_f32_e64 v2, v128, v2
	v_add_f32_e64 v3, v129, v3
	v_add_f32_e64 v2, v130, v2
	v_add_f32_e64 v3, v131, v3
	v_add_f32_e32 v2, v132, v2
	v_add_f32_e32 v3, v133, v3
	v_mfma_f32_32x32x16_bf16 v[96:111], v[64:67], v[52:55], v[96:111]
	v_add_f32_e64 v2, v134, v2
	v_add_f32_e64 v3, v135, v3
	v_cvt_pk_bf16_f32 v64, v136, v137
	v_add_f32_e64 v2, v136, v2
	v_add_f32_e64 v3, v137, v3
	v_cvt_pk_bf16_f32 v65, v148, v149
	v_add_f32_e32 v2, v148, v2
	v_add_f32_e32 v3, v149, v3
	v_cvt_pk_bf16_f32 v66, v150, v151
	v_add_f32_e32 v2, v150, v2
	v_add_f32_e32 v3, v151, v3
	s_waitcnt lgkmcnt(1)
	v_mfma_f32_32x32x16_bf16 v[80:95], v[72:75], v[52:55], v[80:95]
	v_add_f32_e64 v2, v152, v2
	v_add_f32_e64 v3, v153, v3
	v_cvt_pk_bf16_f32 v67, v152, v153
	v_add_f32_e32 v0, v2, v3
	v_add_f32_e32 v0, v8, v0
	v_mfma_f32_32x32x16_bf16 v[96:111], v[60:63], v[64:67], v[96:111]
	s_waitcnt lgkmcnt(0)
	v_mfma_f32_32x32x16_bf16 v[80:95], v[76:79], v[64:67], v[80:95]

; __device__ __forceinline__ float fast_exp2(float x) { return __builtin_amdgcn_exp2f(x); }
; template <int MODE>
; __device__ __forceinline__ void attn_unit(const Params& P, int b, int h, int qb, unsigned char* smem) {
;     ...
;       {
;         const f32x2_t m2 = {m_run, m_run};
;         f32x2_t ps2 = {0.f, 0.f};
; #pragma unroll
;         for (int kb = 0; kb < 2; ++kb)
; #pragma unroll
;           for (int i = 0; i < 8; ++i) {
;             f32x2_t t = {sacc[kb][2 * i], sacc[kb][2 * i + 1]};
;             t -= m2;
;             f32x2_t e; e[0] = fast_exp2(t[0]); e[1] = fast_exp2(t[1]);
;             ps2 += e;
;             sacc[kb][2 * i] = e[0]; sacc[kb][2 * i + 1] = e[1];
;           }
;         l_run += ps2[0] + ps2[1];
;       }
;       bf16x8 pf[4];
; #pragma unroll
;       for (int a = 0; a < 4; ++a) {
;         const int kb = a >> 1, o8 = (a & 1) * 8;
;         u32x4 u;
;         u.x = pk_bf16(sacc[kb][o8 + 0], sacc[kb][o8 + 1]); u.y = pk_bf16(sacc[kb][o8 + 2], sacc[kb][o8 + 3]);
;         u.z = pk_bf16(sacc[kb][o8 + 4], sacc[kb][o8 + 5]); u.w = pk_bf16(sacc[kb][o8 + 6], sacc[kb][o8 + 7]);
;         pf[a] = __builtin_bit_cast(bf16x8, u);
;       }
; #pragma unroll
;       for (int db = 0; db < 2; ++db)
; #pragma unroll
;         for (int a = 0; a < 4; ++a) {
;           bf16x8 vf = *(const bf16x8*)(smem + cur + 8192 + (32 * db + r) * 128 + (((2 * a + hi) ^ swz) << 4));
;           oacc[db] = __builtin_amdgcn_mfma_f32_32x32x16_bf16(vf, pf[a], oacc[db], 0, 0, 0);
;         }
.LBB0_875:
	v_sub_f32_e32 v2, v2, v146
	v_sub_f32_e32 v3, v3, v146
	v_sub_f32_e32 v4, v4, v146
	v_sub_f32_e32 v5, v5, v146
	v_exp_f32_e32 v76, v2
	v_exp_f32_e32 v77, v3
	v_sub_f32_e32 v2, v8, v146
	v_sub_f32_e32 v3, v9, v146
	v_exp_f32_e32 v74, v4
	v_exp_f32_e32 v78, v2
	v_exp_f32_e32 v79, v3
	v_sub_f32_e32 v2, v10, v146
	v_sub_f32_e32 v3, v11, v146
	v_exp_f32_e32 v75, v5
	v_exp_f32_e32 v190, v2
	v_exp_f32_e32 v191, v3
	v_sub_f32_e32 v2, v12, v146
	v_sub_f32_e32 v3, v13, v146
	v_sub_f32_e32 v6, v6, v146
	v_sub_f32_e32 v7, v7, v146
	v_exp_f32_e32 v192, v2
	v_exp_f32_e32 v193, v3
	v_sub_f32_e32 v2, v14, v146
	v_sub_f32_e32 v3, v15, v146
	v_exp_f32_e32 v72, v6
	v_exp_f32_e32 v14, v2
	v_exp_f32_e32 v15, v3
	v_sub_f32_e32 v2, v64, v146
	v_sub_f32_e32 v3, v65, v146
	v_exp_f32_e32 v73, v7
	v_exp_f32_e32 v194, v2
	v_exp_f32_e32 v195, v3
	v_sub_f32_e32 v2, v48, v146
	v_sub_f32_e32 v3, v49, v146
	v_sub_f32_e32 v48, v52, v146
	v_sub_f32_e32 v49, v53, v146
	v_exp_f32_e32 v196, v2
	v_exp_f32_e32 v197, v3
	v_sub_f32_e32 v2, v66, v146
	v_sub_f32_e32 v3, v67, v146
	v_cvt_pk_bf16_f32 v6, v72, v73
	v_exp_f32_e32 v198, v2
	v_exp_f32_e32 v199, v3
	v_sub_f32_e32 v2, v68, v146
	v_sub_f32_e32 v3, v69, v146
	v_cvt_pk_bf16_f32 v7, v74, v75
	v_exp_f32_e32 v200, v2
	v_exp_f32_e32 v201, v3
	v_sub_f32_e32 v2, v54, v146
	v_sub_f32_e32 v3, v55, v146
	v_cvt_pk_bf16_f32 v8, v76, v77
	v_exp_f32_e32 v202, v2
	v_exp_f32_e32 v203, v3
	v_sub_f32_e32 v2, v56, v146
	v_sub_f32_e32 v3, v57, v146
	v_cvt_pk_bf16_f32 v9, v78, v79
	v_exp_f32_e32 v204, v2
	v_exp_f32_e32 v205, v3
	v_sub_f32_e32 v2, v58, v146
	v_sub_f32_e32 v3, v59, v146
	v_exp_f32_e32 v208, v48
	v_exp_f32_e32 v206, v2
	v_exp_f32_e32 v207, v3
	ds_read_b128 v[2:5], v188 offset:8192
	ds_read_b128 v[10:13], v0 offset:8192
	ds_read_b128 v[52:55], v188 offset:12288
	s_waitcnt lgkmcnt(2)
	v_mfma_f32_32x32x16_bf16 v[32:47], v[2:5], v[6:9], v[32:47]
	ds_read_b128 v[56:59], v187 offset:8192
	ds_read_b128 v[60:63], v0 offset:12288
	v_cvt_pk_bf16_f32 v2, v190, v191
	v_cvt_pk_bf16_f32 v3, v192, v193
	v_cvt_pk_bf16_f32 v4, v14, v15
	v_cvt_pk_bf16_f32 v5, v194, v195
	v_exp_f32_e32 v209, v49
	v_sub_f32_e32 v68, v50, v146
	v_sub_f32_e32 v69, v51, v146
	s_waitcnt lgkmcnt(2)
	v_mfma_f32_32x32x16_bf16 v[16:31], v[52:55], v[6:9], v[16:31]
	ds_read_b128 v[48:51], v189 offset:8192
	ds_read_b128 v[64:67], v187 offset:12288
	v_add_f32_e64 v6, v72, 0
	v_add_f32_e64 v7, v73, 0
	v_exp_f32_e32 v210, v68
	v_exp_f32_e32 v211, v69
	ds_read_b128 v[68:71], v189 offset:12288
	v_add_f32_e32 v6, v74, v6
	v_add_f32_e32 v7, v75, v7
	v_mfma_f32_32x32x16_bf16 v[32:47], v[10:13], v[2:5], v[32:47]
	v_cvt_pk_bf16_f32 v10, v196, v197
	v_cvt_pk_bf16_f32 v11, v198, v199
	v_cvt_pk_bf16_f32 v12, v200, v201
	v_cvt_pk_bf16_f32 v13, v202, v203
	v_add_f32_e64 v6, v76, v6
	v_add_f32_e64 v7, v77, v7
	s_waitcnt lgkmcnt(3)
	v_mfma_f32_32x32x16_bf16 v[16:31], v[60:63], v[2:5], v[16:31]
	v_add_f32_e64 v2, v78, v6
	v_add_f32_e64 v3, v79, v7
	v_add_f32_e64 v2, v190, v2
	v_add_f32_e64 v3, v191, v3
	v_add_f32_e64 v2, v192, v2
	v_add_f32_e64 v3, v193, v3
	v_add_f32_e32 v2, v14, v2
	v_add_f32_e32 v3, v15, v3
	v_mfma_f32_32x32x16_bf16 v[32:47], v[56:59], v[10:13], v[32:47]
	v_add_f32_e64 v2, v194, v2
	v_add_f32_e64 v3, v195, v3
	v_cvt_pk_bf16_f32 v56, v204, v205
	v_add_f32_e64 v2, v196, v2
	v_add_f32_e64 v3, v197, v3
	v_cvt_pk_bf16_f32 v57, v206, v207
	v_cvt_pk_bf16_f32 v58, v208, v209
	v_cvt_pk_bf16_f32 v59, v210, v211
	v_add_f32_e32 v2, v198, v2
	v_add_f32_e32 v3, v199, v3
	s_waitcnt lgkmcnt(1)
	v_mfma_f32_32x32x16_bf16 v[16:31], v[64:67], v[10:13], v[16:31]
	v_add_f32_e64 v2, v200, v2
	v_add_f32_e64 v3, v201, v3
	v_add_f32_e64 v2, v202, v2
	v_add_f32_e64 v3, v203, v3
	v_add_f32_e64 v2, v204, v2
	v_add_f32_e64 v3, v205, v3
	v_add_f32_e32 v2, v206, v2
	v_add_f32_e32 v3, v207, v3
	v_mfma_f32_32x32x16_bf16 v[32:47], v[48:51], v[56:59], v[32:47]
	v_add_f32_e64 v2, v208, v2
	v_add_f32_e64 v3, v209, v3
	v_add_f32_e64 v2, v210, v2
	v_add_f32_e64 v3, v211, v3
	v_add_f32_e32 v0, v2, v3
	v_add_f32_e32 v176, v176, v0
	s_waitcnt lgkmcnt(0)
	v_mfma_f32_32x32x16_bf16 v[16:31], v[68:71], v[56:59], v[16:31]

; __device__ __forceinline__ float fast_exp2(float x) { return __builtin_amdgcn_exp2f(x); }
; template <int MODE>
; __device__ __forceinline__ void attn_unit(const Params& P, int b, int h, int qb, unsigned char* smem) {
;     ...
;       {
;         const f32x2_t m2 = {m_run, m_run};
;         f32x2_t ps2 = {0.f, 0.f};
; #pragma unroll
;         for (int kb = 0; kb < 2; ++kb)
; #pragma unroll
;           for (int i = 0; i < 8; ++i) {
;             f32x2_t t = {sacc[kb][2 * i], sacc[kb][2 * i + 1]};
;             t -= m2;
;             f32x2_t e; e[0] = fast_exp2(t[0]); e[1] = fast_exp2(t[1]);
;             ps2 += e;
;             sacc[kb][2 * i] = e[0]; sacc[kb][2 * i + 1] = e[1];
;           }
;         l_run += ps2[0] + ps2[1];
;       }
;       bf16x8 pf[4];
; #pragma unroll
;       for (int a = 0; a < 4; ++a) {
;         const int kb = a >> 1, o8 = (a & 1) * 8;
;         u32x4 u;
;         u.x = pk_bf16(sacc[kb][o8 + 0], sacc[kb][o8 + 1]); u.y = pk_bf16(sacc[kb][o8 + 2], sacc[kb][o8 + 3]);
;         u.z = pk_bf16(sacc[kb][o8 + 4], sacc[kb][o8 + 5]); u.w = pk_bf16(sacc[kb][o8 + 6], sacc[kb][o8 + 7]);
;         pf[a] = __builtin_bit_cast(bf16x8, u);
;       }
; #pragma unroll
;       for (int db = 0; db < 2; ++db)
; #pragma unroll
;         for (int a = 0; a < 4; ++a) {
;           bf16x8 vf = *(const bf16x8*)(smem + cur + 8192 + (32 * db + r) * 128 + (((2 * a + hi) ^ swz) << 4));
;           oacc[db] = __builtin_amdgcn_mfma_f32_32x32x16_bf16(vf, pf[a], oacc[db], 0, 0, 0);
;         }
.LBB0_1623:
	v_sub_f32_e32 v32, v32, v118
	v_sub_f32_e32 v33, v33, v118
	v_sub_f32_e32 v48, v48, v118
	v_sub_f32_e32 v49, v49, v118
	v_exp_f32_e32 v140, v32
	v_exp_f32_e32 v141, v33
	v_sub_f32_e32 v32, v34, v118
	v_sub_f32_e32 v33, v35, v118
	v_exp_f32_e32 v90, v48
	v_exp_f32_e32 v142, v32
	v_exp_f32_e32 v143, v33
	v_sub_f32_e32 v32, v36, v118
	v_sub_f32_e32 v33, v37, v118
	v_exp_f32_e32 v91, v49
	v_sub_f32_e32 v48, v50, v118
	v_sub_f32_e32 v49, v51, v118
	v_exp_f32_e32 v144, v32
	v_exp_f32_e32 v145, v33
	v_sub_f32_e32 v32, v38, v118
	v_sub_f32_e32 v33, v39, v118
	v_exp_f32_e32 v92, v48
	v_exp_f32_e32 v93, v49
	v_sub_f32_e32 v48, v52, v118
	v_sub_f32_e32 v49, v53, v118
	v_exp_f32_e32 v146, v32
	v_exp_f32_e32 v147, v33
	v_sub_f32_e32 v32, v40, v118
	v_sub_f32_e32 v33, v41, v118
	v_exp_f32_e32 v94, v48
	v_exp_f32_e32 v95, v49
	v_sub_f32_e32 v48, v54, v118
	v_sub_f32_e32 v49, v55, v118
	v_exp_f32_e32 v148, v32
	v_exp_f32_e32 v149, v33
	v_sub_f32_e32 v32, v42, v118
	v_sub_f32_e32 v33, v43, v118
	v_exp_f32_e32 v130, v48
	v_exp_f32_e32 v131, v49
	v_sub_f32_e32 v48, v56, v118
	v_sub_f32_e32 v49, v57, v118
	v_exp_f32_e32 v150, v32
	v_exp_f32_e32 v151, v33
	ds_read_b128 v[32:35], v85 offset:8192
	v_exp_f32_e32 v132, v48
	v_exp_f32_e32 v133, v49
	v_sub_f32_e32 v48, v58, v118
	v_sub_f32_e32 v49, v59, v118
	v_cvt_pk_bf16_f32 v36, v90, v91
	v_exp_f32_e32 v134, v48
	v_exp_f32_e32 v135, v49
	v_sub_f32_e32 v48, v60, v118
	v_sub_f32_e32 v49, v61, v118
	v_cvt_pk_bf16_f32 v37, v92, v93
	v_exp_f32_e32 v136, v48
	v_exp_f32_e32 v137, v49
	v_sub_f32_e32 v48, v62, v118
	v_sub_f32_e32 v49, v63, v118
	v_cvt_pk_bf16_f32 v38, v94, v95
	v_exp_f32_e32 v138, v48
	v_exp_f32_e32 v139, v49
	ds_read_b128 v[40:43], v86 offset:8192
	ds_read_b128 v[48:51], v85 offset:12288
	v_cvt_pk_bf16_f32 v39, v130, v131
	ds_read_b128 v[52:55], v87 offset:8192
	ds_read_b128 v[56:59], v86 offset:12288
	s_waitcnt lgkmcnt(4)
	v_mfma_f32_32x32x16_bf16 v[16:31], v[32:35], v[36:39], v[16:31]
	v_cvt_pk_bf16_f32 v32, v132, v133
	v_cvt_pk_bf16_f32 v33, v134, v135
	v_cvt_pk_bf16_f32 v34, v136, v137
	v_cvt_pk_bf16_f32 v35, v138, v139
	v_add_f32_e64 v44, v44, -v118
	v_add_f32_e64 v45, v45, -v118
	v_sub_f32_e32 v154, v46, v118
	v_sub_f32_e32 v155, v47, v118
	v_exp_f32_e32 v152, v44
	s_waitcnt lgkmcnt(2)
	v_mfma_f32_32x32x16_bf16 v[0:15], v[48:51], v[36:39], v[0:15]
	v_exp_f32_e32 v153, v45
	ds_read_b128 v[44:47], v88 offset:8192
	ds_read_b128 v[60:63], v87 offset:12288
	v_add_f32_e32 v36, 0, v90
	v_add_f32_e32 v37, 0, v91
	ds_read_b128 v[86:89], v88 offset:12288
	v_add_f32_e32 v36, v92, v36
	v_add_f32_e32 v37, v93, v37
	v_exp_f32_e32 v154, v154
	v_add_f32_e32 v36, v94, v36
	v_add_f32_e32 v37, v95, v37
	v_mfma_f32_32x32x16_bf16 v[16:31], v[40:43], v[32:35], v[16:31]
	v_cvt_pk_bf16_f32 v40, v140, v141
	v_cvt_pk_bf16_f32 v41, v142, v143
	v_cvt_pk_bf16_f32 v42, v144, v145
	v_cvt_pk_bf16_f32 v43, v146, v147
	v_exp_f32_e32 v155, v155
	s_waitcnt lgkmcnt(3)
	v_mfma_f32_32x32x16_bf16 v[0:15], v[56:59], v[32:35], v[0:15]
	v_add_f32_e64 v32, v130, v36
	v_add_f32_e64 v33, v131, v37
	v_add_f32_e64 v32, v132, v32
	v_add_f32_e64 v33, v133, v33
	v_add_f32_e64 v32, v134, v32
	v_add_f32_e64 v33, v135, v33
	v_add_f32_e32 v32, v136, v32
	v_add_f32_e32 v33, v137, v33
	v_mfma_f32_32x32x16_bf16 v[16:31], v[52:55], v[40:43], v[16:31]
	v_add_f32_e64 v32, v138, v32
	v_add_f32_e64 v33, v139, v33
	v_cvt_pk_bf16_f32 v52, v148, v149
	v_add_f32_e64 v32, v140, v32
	v_add_f32_e64 v33, v141, v33
	v_cvt_pk_bf16_f32 v53, v150, v151
	v_cvt_pk_bf16_f32 v54, v152, v153
	v_cvt_pk_bf16_f32 v55, v154, v155
	v_add_f32_e32 v32, v142, v32
	v_add_f32_e32 v33, v143, v33
	s_waitcnt lgkmcnt(1)
	v_mfma_f32_32x32x16_bf16 v[0:15], v[60:63], v[40:43], v[0:15]
	v_add_f32_e64 v32, v144, v32
	v_add_f32_e64 v33, v145, v33
	v_add_f32_e64 v32, v146, v32
	v_add_f32_e64 v33, v147, v33
	v_add_f32_e64 v32, v148, v32
	v_add_f32_e64 v33, v149, v33
	v_add_f32_e32 v32, v150, v32
	v_add_f32_e32 v33, v151, v33
	v_mfma_f32_32x32x16_bf16 v[16:31], v[44:47], v[52:55], v[16:31]
	v_add_f32_e64 v32, v152, v32
	v_add_f32_e64 v33, v153, v33
	v_add_f32_e64 v32, v154, v32
	v_add_f32_e64 v33, v155, v33
	v_add_f32_e32 v32, v32, v33
	v_add_f32_e32 v123, v123, v32
	s_waitcnt lgkmcnt(0)
	v_mfma_f32_32x32x16_bf16 v[0:15], v[86:89], v[52:55], v[0:15]

; __device__ __forceinline__ float fast_exp2(float x) { return __builtin_amdgcn_exp2f(x); }
; template <int MODE>
; __device__ __forceinline__ void attn_unit(const Params& P, int b, int h, int qb, unsigned char* smem) {
;     ...
;       {
;         const f32x2_t m2 = {m_run, m_run};
;         f32x2_t ps2 = {0.f, 0.f};
; #pragma unroll
;         for (int kb = 0; kb < 2; ++kb)
; #pragma unroll
;           for (int i = 0; i < 8; ++i) {
;             f32x2_t t = {sacc[kb][2 * i], sacc[kb][2 * i + 1]};
;             t -= m2;
;             f32x2_t e; e[0] = fast_exp2(t[0]); e[1] = fast_exp2(t[1]);
;             ps2 += e;
;             sacc[kb][2 * i] = e[0]; sacc[kb][2 * i + 1] = e[1];
;           }
;         l_run += ps2[0] + ps2[1];
;       }
;       bf16x8 pf[4];
; #pragma unroll
;       for (int a = 0; a < 4; ++a) {
;         const int kb = a >> 1, o8 = (a & 1) * 8;
;         u32x4 u;
;         u.x = pk_bf16(sacc[kb][o8 + 0], sacc[kb][o8 + 1]); u.y = pk_bf16(sacc[kb][o8 + 2], sacc[kb][o8 + 3]);
;         u.z = pk_bf16(sacc[kb][o8 + 4], sacc[kb][o8 + 5]); u.w = pk_bf16(sacc[kb][o8 + 6], sacc[kb][o8 + 7]);
;         pf[a] = __builtin_bit_cast(bf16x8, u);
;       }
; #pragma unroll
;       for (int db = 0; db < 2; ++db)
; #pragma unroll
;         for (int a = 0; a < 4; ++a) {
;           bf16x8 vf = *(const bf16x8*)(smem + cur + 8192 + (32 * db + r) * 128 + (((2 * a + hi) ^ swz) << 4));
;           oacc[db] = __builtin_amdgcn_mfma_f32_32x32x16_bf16(vf, pf[a], oacc[db], 0, 0, 0);
;         }
.LBB0_1632:
	v_sub_f32_e32 v32, v32, v118
	v_sub_f32_e32 v33, v33, v118
	v_sub_f32_e32 v48, v48, v118
	v_sub_f32_e32 v49, v49, v118
	v_exp_f32_e32 v138, v32
	v_exp_f32_e32 v139, v33
	v_sub_f32_e32 v32, v34, v118
	v_sub_f32_e32 v33, v35, v118
	v_exp_f32_e32 v102, v48
	v_exp_f32_e32 v140, v32
	v_exp_f32_e32 v141, v33
	v_sub_f32_e32 v32, v36, v118
	v_sub_f32_e32 v33, v37, v118
	v_exp_f32_e32 v103, v49
	v_sub_f32_e32 v48, v50, v118
	v_sub_f32_e32 v49, v51, v118
	v_exp_f32_e32 v142, v32
	v_exp_f32_e32 v143, v33
	v_sub_f32_e32 v32, v38, v118
	v_sub_f32_e32 v33, v39, v118
	v_exp_f32_e32 v104, v48
	v_exp_f32_e32 v105, v49
	v_sub_f32_e32 v48, v52, v118
	v_sub_f32_e32 v49, v53, v118
	v_exp_f32_e32 v144, v32
	v_exp_f32_e32 v145, v33
	v_sub_f32_e32 v32, v40, v118
	v_sub_f32_e32 v33, v41, v118
	v_exp_f32_e32 v106, v48
	v_exp_f32_e32 v107, v49
	v_sub_f32_e32 v48, v54, v118
	v_sub_f32_e32 v49, v55, v118
	v_exp_f32_e32 v146, v32
	v_exp_f32_e32 v147, v33
	v_sub_f32_e32 v32, v42, v118
	v_sub_f32_e32 v33, v43, v118
	v_exp_f32_e32 v108, v48
	v_exp_f32_e32 v109, v49
	v_sub_f32_e32 v48, v56, v118
	v_sub_f32_e32 v49, v57, v118
	v_exp_f32_e32 v148, v32
	v_exp_f32_e32 v149, v33
	ds_read_b128 v[32:35], v114 offset:8192
	v_exp_f32_e32 v110, v48
	v_exp_f32_e32 v111, v49
	v_sub_f32_e32 v48, v58, v118
	v_sub_f32_e32 v49, v59, v118
	v_cvt_pk_bf16_f32 v36, v102, v103
	v_exp_f32_e32 v128, v48
	v_exp_f32_e32 v129, v49
	v_sub_f32_e32 v48, v60, v118
	v_sub_f32_e32 v49, v61, v118
	v_cvt_pk_bf16_f32 v37, v104, v105
	v_exp_f32_e32 v134, v48
	v_exp_f32_e32 v135, v49
	v_sub_f32_e32 v48, v62, v118
	v_sub_f32_e32 v49, v63, v118
	v_cvt_pk_bf16_f32 v38, v106, v107
	v_exp_f32_e32 v136, v48
	v_exp_f32_e32 v137, v49
	ds_read_b128 v[40:43], v127 offset:8192
	ds_read_b128 v[48:51], v114 offset:12288
	v_cvt_pk_bf16_f32 v39, v108, v109
	ds_read_b128 v[52:55], v126 offset:8192
	ds_read_b128 v[56:59], v127 offset:12288
	s_waitcnt lgkmcnt(4)
	v_mfma_f32_32x32x16_bf16 v[80:95], v[32:35], v[36:39], v[80:95]
	v_cvt_pk_bf16_f32 v32, v110, v111
	v_cvt_pk_bf16_f32 v33, v128, v129
	v_cvt_pk_bf16_f32 v34, v134, v135
	v_cvt_pk_bf16_f32 v35, v136, v137
	v_add_f32_e64 v44, v44, -v118
	v_add_f32_e64 v45, v45, -v118
	v_sub_f32_e32 v98, v46, v118
	v_sub_f32_e32 v99, v47, v118
	v_exp_f32_e32 v150, v44
	s_waitcnt lgkmcnt(2)
	v_mfma_f32_32x32x16_bf16 v[64:79], v[48:51], v[36:39], v[64:79]
	v_add_f32_e64 v36, v102, 0
	v_add_f32_e64 v37, v103, 0
	v_exp_f32_e32 v151, v45
	v_add_f32_e32 v36, v104, v36
	v_add_f32_e32 v37, v105, v37
	ds_read_b128 v[44:47], v125 offset:8192
	ds_read_b128 v[60:63], v126 offset:12288
	v_add_f32_e32 v36, v106, v36
	v_add_f32_e32 v37, v107, v37
	v_exp_f32_e32 v126, v98
	v_exp_f32_e32 v127, v99
	v_mfma_f32_32x32x16_bf16 v[80:95], v[40:43], v[32:35], v[80:95]
	v_cvt_pk_bf16_f32 v40, v138, v139
	v_cvt_pk_bf16_f32 v41, v140, v141
	v_cvt_pk_bf16_f32 v42, v142, v143
	v_cvt_pk_bf16_f32 v43, v144, v145
	ds_read_b128 v[98:101], v125 offset:12288
	s_waitcnt lgkmcnt(3)
	v_mfma_f32_32x32x16_bf16 v[64:79], v[56:59], v[32:35], v[64:79]
	v_add_f32_e64 v32, v108, v36
	v_add_f32_e64 v33, v109, v37
	v_add_f32_e64 v32, v110, v32
	v_add_f32_e64 v33, v111, v33
	v_add_f32_e64 v32, v128, v32
	v_add_f32_e64 v33, v129, v33
	v_add_f32_e32 v32, v134, v32
	v_add_f32_e32 v33, v135, v33
	v_mfma_f32_32x32x16_bf16 v[80:95], v[52:55], v[40:43], v[80:95]
	v_add_f32_e64 v32, v136, v32
	v_add_f32_e64 v33, v137, v33
	v_cvt_pk_bf16_f32 v52, v146, v147
	v_add_f32_e64 v32, v138, v32
	v_add_f32_e64 v33, v139, v33
	v_cvt_pk_bf16_f32 v53, v148, v149
	v_add_f32_e32 v32, v140, v32
	v_add_f32_e32 v33, v141, v33
	v_cvt_pk_bf16_f32 v54, v150, v151
	v_add_f32_e32 v32, v142, v32
	v_add_f32_e32 v33, v143, v33
	s_waitcnt lgkmcnt(1)
	v_mfma_f32_32x32x16_bf16 v[64:79], v[60:63], v[40:43], v[64:79]
	v_add_f32_e64 v32, v144, v32
	v_add_f32_e64 v33, v145, v33
	v_cvt_pk_bf16_f32 v55, v126, v127
	v_add_f32_e64 v32, v146, v32
	v_add_f32_e64 v33, v147, v33
	v_add_f32_e32 v32, v148, v32
	v_add_f32_e32 v33, v149, v33
	s_nop 0
	v_add_f32_e32 v32, v150, v32
	v_add_f32_e32 v33, v151, v33
	v_mfma_f32_32x32x16_bf16 v[80:95], v[44:47], v[52:55], v[80:95]
	v_add_f32_e64 v32, v126, v32
	v_add_f32_e64 v33, v127, v33
	v_add_f32_e32 v32, v32, v33
	v_add_f32_e32 v32, v96, v32
	s_waitcnt lgkmcnt(0)
	v_mfma_f32_32x32x16_bf16 v[64:79], v[98:101], v[52:55], v[64:79]
